# P0 weight-transpose loop rotated: LDS read/pack/store half of tile i runs after the decode + load issue of tile i+1 (own register bank), so the next tile's weight-load latency overlaps it; load wait +
# speedup vs baseline: 1.0099x; 1.0034x over previous
; __global__ void __launch_bounds__(512) mega(Params p) {
;     ...
;     for (int it = bid; it < 4 * 1630; it += nblk) {
;       const int l = it / 1630; int r = it % 1630;
;       const float* src; int ldsrc; bf16_t* dst; int K; const float* gain = nullptr; int kind; int kt, nt;
;       if (r < 384) { kind = 0; src = p.in[3] + (size_t)l * 1024 * 2866; ldsrc = 2866; dst = cx.win + (size_t)l * NIN * 1024; K = 1024; gain = p.in[2] + l * 1024; kt = r / 24; nt = r % 24; }
;       else if (r < 512) { r -= 384; kind = 1; src = p.in[15] + (size_t)l * 1024 * 1024; ldsrc = 1024; dst = cx.wout + (size_t)l * 1024 * 1024; K = 1024; kt = r / 8; nt = r % 8; }
;       else if (r < 1024) { r -= 512; kind = 2; src = p.in[17] + (size_t)l * 1024 * 4096; ldsrc = 4096; dst = cx.wup + (size_t)l * 4096 * 1024; K = 1024; gain = p.in[16] + l * 1024; kt = r / 32; nt = r % 32; }
;       else if (r < 1536) { r -= 1024; kind = 3; src = p.in[18] + (size_t)l * 4096 * 1024; ldsrc = 1024; dst = cx.wdown + (size_t)l * 1024 * 4096; K = 4096; kt = r / 8; nt = r % 8; }
;       else if (r < 1568) { r -= 1536; kind = 4; src = p.in[5] + (size_t)l * 2048 * 128; ldsrc = 128; dst = cx.w1 + (size_t)(l * 2 + 0) * 128 * 2048; K = 2048; kt = r; nt = 0; }
;       else if (r < 1600) { r -= 1568; kind = 5; src = p.in[8] + (size_t)l * 2048 * 128; ldsrc = 128; dst = cx.w1 + (size_t)(l * 2 + 1) * 128 * 2048; K = 2048; kt = r; nt = 0; }
;       else if (r < 1602) { r -= 1600; kind = 6; src = p.in[6] + (size_t)l * 128 * 64; ldsrc = 64; dst = cx.w2 + (size_t)(l * 2 + 0) * 128 * 128; K = 128; kt = r; nt = 0; }
;       else if (r < 1604) { r -= 1602; kind = 7; src = p.in[9] + (size_t)l * 128 * 64; ldsrc = 64; dst = cx.w2 + (size_t)(l * 2 + 1) * 128 * 128; K = 128; kt = r; nt = 0; }
;       else if (r < 1620) { r -= 1604; kind = 8; src = p.in[11] + (size_t)l * 256 * 480; ldsrc = 480; dst = cx.wuq + (size_t)l * 512 * 256; K = 256; gain = p.in[10] + l * 256; kt = r / 4; nt = r % 4; }
;       else { r -= 1620; kind = 9; src = p.in[13] + (size_t)l * 128 * 640; ldsrc = 640; dst = cx.wukv + (size_t)l * 640 * 128; K = 128; gain = p.in[12] + l * 128; kt = r / 5; nt = r % 5; }
;       transpose_tile(src, ldsrc, dst, K, kt * 64, nt * 128, gain, kind, lt, wv);
.LBB0_2:
	s_or_b64 exec, exec, s[2:3]
	s_load_dwordx4 s[4:7], s[78:79], 0xa0
	s_waitcnt lgkmcnt(0)
	s_add_u32 s0, s6, 0x18d00000
	v_writelane_b32 v252, s0, 47
	s_addc_u32 s0, s7, 0
	v_writelane_b32 v252, s0, 48
	s_add_u32 s0, s6, 0x1a500000
	v_writelane_b32 v252, s0, 49
	s_addc_u32 s0, s7, 0
	v_writelane_b32 v252, s0, 50
	s_add_u32 s0, s6, 0x1ad00000
	v_writelane_b32 v252, s0, 51
	s_addc_u32 s0, s7, 0
	v_writelane_b32 v252, s0, 52
	s_add_u32 s0, s6, 0x1cd00000
	v_writelane_b32 v252, s0, 53
	s_addc_u32 s0, s7, 0
	v_writelane_b32 v252, s0, 54
	s_add_u32 s0, s6, 0x1ed00000
	v_writelane_b32 v252, s0, 55
	s_addc_u32 s0, s7, 0
	v_writelane_b32 v252, s0, 56
	s_add_u32 s0, s6, 0x1f100000
	v_writelane_b32 v252, s0, 57
	s_addc_u32 s0, s7, 0
	v_writelane_b32 v252, s0, 58
	s_add_u32 s0, s6, 0x1f200000
	v_writelane_b32 v252, s0, 59
	s_addc_u32 s0, s7, 0
	v_writelane_b32 v252, s0, 60
	s_add_u32 s0, s6, 0x1f300000
	v_writelane_b32 v252, s0, 61
	s_addc_u32 s0, s7, 0
	v_writelane_b32 v252, s0, 62
	s_cmpk_gt_i32 s76, 0x1977
	s_cbranch_scc1 .LBB0_195
	s_movk_i32 s28, 0x392
	s_movk_i32 s29, 0x3c0
	s_movk_i32 s30, 0x1c0
	s_movk_i32 s31, 0xffc0
	v_mov_b32_e32 v5, 0
	s_movk_i32 s33, 0x104
	s_mov_b32 s34, s76
	s_mov_b32 s56, 0
	s_mov_b32 s67, 0
	s_branch .LBB0_5
.LBB0_4:
	s_cmp_eq_u32 s56, 0
	s_cbranch_scc1 .Ltr_W
	s_mov_b64 s[68:69], exec
	s_or_b64 exec, exec, s[18:19]
.Ltr_Cp:
	s_waitcnt lgkmcnt(0)
	s_barrier
	s_lshl_b64 s[60:61], s[62:63], 1
	ds_read2_b32 v[146:147], v143 offset1:1
	ds_read2_b32 v[148:149], v143 offset0:2 offset1:3
	ds_read2_b32 v[152:153], v143 offset0:4 offset1:5
	ds_read2_b32 v[154:155], v143 offset0:6 offset1:7
	s_add_u32 s58, s58, s60
	s_addc_u32 s59, s59, s61
	v_lshl_add_u64 v[156:157], s[58:59], 0, v[144:145]
	v_add_u32_e32 v144, s57, v151
	v_ashrrev_i32_e32 v151, 31, v144
	s_waitcnt lgkmcnt(3)
	v_cvt_pk_bf16_f32 v146, v146, v147
	s_waitcnt lgkmcnt(2)
	v_cvt_pk_bf16_f32 v147, v148, v149
	s_waitcnt lgkmcnt(1)
	v_cvt_pk_bf16_f32 v148, v152, v153
	s_waitcnt lgkmcnt(0)
	v_cvt_pk_bf16_f32 v149, v154, v155
	v_mul_lo_u32 v151, s64, v151
	v_mul_lo_u32 v154, s65, v144
	v_mad_u64_u32 v[152:153], s[58:59], s64, v144, 0
	v_add3_u32 v153, v153, v151, v154
	v_add_u32_e32 v151, 0x4100, v143
	v_add_u32_e32 v158, 0x4108, v143
	v_add_u32_e32 v160, 0x4110, v143
	v_add_u32_e32 v143, 0x4118, v143
	ds_read2_b32 v[154:155], v151 offset1:1
	ds_read2_b32 v[158:159], v158 offset1:1
	ds_read2_b32 v[160:161], v160 offset1:1
	ds_read2_b32 v[162:163], v143 offset1:1
	v_add_u32_e32 v143, 64, v144
	v_lshl_add_u64 v[152:153], v[152:153], 1, v[156:157]
	v_ashrrev_i32_e32 v144, 31, v143
	global_store_dwordx4 v[152:153], v[146:149], off
	v_mul_lo_u32 v144, s64, v144
	v_mul_lo_u32 v151, s65, v143
	v_mad_u64_u32 v[152:153], s[58:59], s64, v143, 0
	v_add3_u32 v153, v153, v144, v151
	v_lshl_add_u64 v[152:153], v[152:153], 1, v[156:157]
	s_waitcnt lgkmcnt(3)
	v_cvt_pk_bf16_f32 v146, v154, v155
	s_waitcnt lgkmcnt(2)
	v_cvt_pk_bf16_f32 v147, v158, v159
	s_waitcnt lgkmcnt(1)
	v_cvt_pk_bf16_f32 v148, v160, v161
	s_waitcnt lgkmcnt(0)
	v_cvt_pk_bf16_f32 v149, v162, v163
	global_store_dwordx4 v[152:153], v[146:149], off
	s_barrier
	s_cmp_eq_u32 s67, 1
	s_cbranch_scc1 .LBB0_195
	s_mov_b64 exec, s[68:69]
.Ltr_W:
	s_cmp_eq_u32 s56, 0
	s_cbranch_scc1 .Ltr_w0
	s_waitcnt vmcnt(2)
	s_branch .Ltr_w1

; DEVI int map_row(int kind, int k) { return kind == 4 ? (k & ~63) + permd(k & 63, 8) : k; }
; DEVI void transpose_tile(const float* __restrict__ src, int ldsrc, bf16_t* __restrict__ dst, int K, int k0, int n0,
;                          const float* __restrict__ gain, int kind, float* lt, int wv) {
;     ...
;   for (int i = 0; i < 16; ++i) {
;     const int kk = kq + i * 4;
;     v[i] = 0.f;
;     if (sc >= 0) { const int sr = map_row(kind, k0 + kk); v[i] = src[(size_t)sr * ldsrc + sc]; if (gain) v[i] *= gain[k0 + kk]; }
;   }
; #pragma unroll
;   for (int i = 0; i < 16; ++i) lt[nn * 65 + kq + i * 4] = v[i];
; __global__ void __launch_bounds__(512) mega(Params p) {
;     ...
;     for (int it = bid; it < 4 * 1630; it += nblk) {
;       const int l = it / 1630; int r = it % 1630;
;       const float* src; int ldsrc; bf16_t* dst; int K; const float* gain = nullptr; int kind; int kt, nt;
;       if (r < 384) { kind = 0; src = p.in[3] + (size_t)l * 1024 * 2866; ldsrc = 2866; dst = cx.win + (size_t)l * NIN * 1024; K = 1024; gain = p.in[2] + l * 1024; kt = r / 24; nt = r % 24; }
;       else if (r < 512) { r -= 384; kind = 1; src = p.in[15] + (size_t)l * 1024 * 1024; ldsrc = 1024; dst = cx.wout + (size_t)l * 1024 * 1024; K = 1024; kt = r / 8; nt = r % 8; }
;       else if (r < 1024) { r -= 512; kind = 2; src = p.in[17] + (size_t)l * 1024 * 4096; ldsrc = 4096; dst = cx.wup + (size_t)l * 4096 * 1024; K = 1024; gain = p.in[16] + l * 1024; kt = r / 32; nt = r % 32; }
;       else if (r < 1536) { r -= 1024; kind = 3; src = p.in[18] + (size_t)l * 4096 * 1024; ldsrc = 1024; dst = cx.wdown + (size_t)l * 1024 * 4096; K = 4096; kt = r / 8; nt = r % 8; }
;       else if (r < 1568) { r -= 1536; kind = 4; src = p.in[5] + (size_t)l * 2048 * 128; ldsrc = 128; dst = cx.w1 + (size_t)(l * 2 + 0) * 128 * 2048; K = 2048; kt = r; nt = 0; }
;       else if (r < 1600) { r -= 1568; kind = 5; src = p.in[8] + (size_t)l * 2048 * 128; ldsrc = 128; dst = cx.w1 + (size_t)(l * 2 + 1) * 128 * 2048; K = 2048; kt = r; nt = 0; }
;       else if (r < 1602) { r -= 1600; kind = 6; src = p.in[6] + (size_t)l * 128 * 64; ldsrc = 64; dst = cx.w2 + (size_t)(l * 2 + 0) * 128 * 128; K = 128; kt = r; nt = 0; }
;       else if (r < 1604) { r -= 1602; kind = 7; src = p.in[9] + (size_t)l * 128 * 64; ldsrc = 64; dst = cx.w2 + (size_t)(l * 2 + 1) * 128 * 128; K = 128; kt = r; nt = 0; }
.Ltr_w1:
	s_cmp_eq_u32 s66, 0
	s_cbranch_scc1 .Ltr_nog
	v_mul_f32_e32 v28, v28, v6
	v_mul_f32_e32 v4, v4, v120
	v_mul_f32_e32 v14, v14, v121
	v_mul_f32_e32 v15, v15, v122
	v_mul_f32_e32 v16, v16, v123
	v_mul_f32_e32 v17, v17, v124
	v_mul_f32_e32 v18, v18, v125
	v_mul_f32_e32 v19, v19, v126
	v_mul_f32_e32 v20, v20, v127
	v_mul_f32_e32 v21, v21, v128
	v_mul_f32_e32 v22, v22, v129
	v_mul_f32_e32 v23, v23, v130
	v_mul_f32_e32 v24, v24, v131
	v_mul_f32_e32 v25, v25, v132
	v_mul_f32_e32 v26, v26, v133
	v_mul_f32_e32 v27, v27, v134
.Ltr_nog:
	s_or_b64 exec, exec, s[18:19]
	v_mul_u32_u24_e32 v6, 0x104, v12
	v_lshlrev_b32_e32 v7, 2, v13
	v_lshlrev_b32_e32 v3, 3, v3
	v_add3_u32 v6, 0, v6, v7
	v_ashrrev_i32_e32 v11, 3, v11
	v_and_b32_e32 v3, 56, v3
	ds_write2_b32 v6, v4, v14 offset1:4
	ds_write2_b32 v6, v15, v16 offset0:8 offset1:12
	ds_write2_b32 v6, v17, v18 offset0:16 offset1:20
	ds_write2_b32 v6, v19, v20 offset0:24 offset1:28
	ds_write2_b32 v6, v21, v22 offset0:32 offset1:36
	ds_write2_b32 v6, v23, v24 offset0:40 offset1:44
	ds_write2_b32 v6, v25, v26 offset0:48 offset1:52
	ds_write2_b32 v6, v27, v28 offset0:56 offset1:60
	v_lshlrev_b32_e32 v6, 2, v3
	v_lshlrev_b32_e32 v4, 1, v3
	v_mul_lo_u32 v3, v11, s33
	s_ashr_i32 s15, s14, 31
	v_add3_u32 v3, 0, v6, v3
	v_mov_b32_e32 v143, v3
	v_mov_b32_e32 v144, v4
	v_mov_b32_e32 v145, 0
	v_mov_b32_e32 v151, v11
	s_mov_b32 s58, s2
	s_mov_b32 s59, s3
	s_mov_b32 s62, s14
	s_mov_b32 s63, s15
	s_mov_b32 s57, s35
	s_mov_b32 s64, s8
	s_mov_b32 s65, s9
	s_mov_b32 s56, 1
	s_add_i32 s2, s34, 0x100
	s_cmpk_gt_i32 s34, 0x1877
	s_mov_b32 s34, s2
	s_cbranch_scc0 .LBB0_5
	s_mov_b32 s67, 1
	s_branch .Ltr_Cp
.LBB0_5:
	s_mov_b32 s66, 0
	s_mul_hi_i32 s2, s34, 0x2834c543
	s_lshr_b32 s3, s2, 31
	s_ashr_i32 s2, s2, 8
	s_add_i32 s4, s2, s3
	s_mul_i32 s2, s4, 0xfffff9a2
	s_add_i32 s20, s34, s2
	s_cmpk_gt_i32 s20, 0x17f
	s_mov_b64 s[14:15], -1
	s_cbranch_scc0 .LBB0_39
	s_ashr_i32 s5, s4, 31
	s_cmpk_gt_u32 s20, 0x1ff
	s_cbranch_scc0 .LBB0_36
	s_cmpk_gt_u32 s20, 0x3ff
	s_cbranch_scc0 .LBB0_33
	s_cmpk_gt_u32 s20, 0x5ff
	s_cbranch_scc0 .LBB0_30
	s_cmpk_gt_u32 s20, 0x61f
	s_mov_b64 s[16:17], -1
	s_cbranch_scc0 .LBB0_28
	s_mul_i32 s2, s4, 0x65e
	s_sub_i32 s16, s34, s2
	s_cmpk_gt_u32 s20, 0x63f
	s_cbranch_scc0 .LBB0_25
	s_cmpk_gt_u32 s20, 0x641
	s_cbranch_scc0 .LBB0_22
	s_cmpk_gt_u32 s20, 0x643
	s_cbranch_scc0 .LBB0_19
	s_cmpk_gt_u32 s20, 0x653
	s_mov_b64 s[8:9], -1
	s_cbranch_scc0 .LBB0_15
	s_load_dwordx16 s[36:51], s[78:79], 0x40
	s_add_i32 s12, s20, 0xfffff9ac
	s_mul_i32 s3, s4, 0x50000
	s_mul_hi_i32 s2, s4, 0x50000
	v_readlane_b32 s0, v252, 61
	s_waitcnt lgkmcnt(0)
	s_add_u32 s6, s46, s3
	s_addc_u32 s7, s47, s2
	s_mul_i32 s2, s4, 0x28000
	s_mul_hi_i32 s3, s4, 0x28000
	s_add_u32 s2, s0, s2
	v_readlane_b32 s0, v252, 62
	s_addc_u32 s3, s0, s3
	s_lshl_b32 s8, s4, 7
	s_ashr_i32 s9, s8, 31
	s_lshl_b64 s[8:9], s[8:9], 2
	s_add_u32 s10, s44, s8
	s_addc_u32 s11, s45, s9
	s_cmp_gt_u32 s12, 4
	s_cselect_b64 s[8:9], -1, 0
	v_cndmask_b32_e64 v3, 0, 1, s[8:9]
	s_add_i32 s8, s20, 0xfffff9a7
	s_cmp_lt_u32 s12, 5
	v_readfirstlane_b32 s36, v3
	s_cselect_b32 s22, s12, s8
	s_mov_b64 s[8:9], 0

; DEVI int map_row(int kind, int k) { return kind == 4 ? (k & ~63) + permd(k & 63, 8) : k; }
; DEVI void transpose_tile(const float* __restrict__ src, int ldsrc, bf16_t* __restrict__ dst, int K, int k0, int n0,
;                          const float* __restrict__ gain, int kind, float* lt, int wv) {
;     ...
;   for (int i = 0; i < 16; ++i) {
;     const int kk = kq + i * 4;
;     v[i] = 0.f;
;     if (sc >= 0) { const int sr = map_row(kind, k0 + kk); v[i] = src[(size_t)sr * ldsrc + sc]; if (gain) v[i] *= gain[k0 + kk]; }
;   }
.LBB0_193:
	v_ashrrev_i32_e32 v28, 31, v7
	v_mul_lo_u32 v30, s13, v7
	v_mul_lo_u32 v31, s12, v28
	v_mad_u64_u32 v[28:29], s[4:5], s12, v7, 0
	v_add3_u32 v29, v29, v31, v30
	v_lshl_add_u64 v[8:9], v[28:29], 2, v[8:9]
	global_load_dword v28, v[8:9], off
	s_andn2_b64 vcc, exec, s[16:17]
	s_cbranch_vccnz .LBB0_4
	v_ashrrev_i32_e32 v7, 31, v6
	v_lshl_add_u64 v[6:7], v[6:7], 2, s[10:11]
	global_load_dword v6, v[6:7], off offset:240
	s_mov_b32 s66, 1
	s_branch .LBB0_4
